# v42 + HGRN2 output-pass MFMA chains: LDS fragment reads software-pipelined 2-3 steps ahead (counted lgkmcnt)
# speedup vs baseline: 1.0038x; 1.0038x over previous
.LBB0_2677:
	s_andn2_b64 vcc, exec, s[62:63]
	s_cbranch_vccnz .LBB0_2679
	ds_read_b128 v[32:35], v90 offset:17408
	ds_read_b128 v[36:39], v91
	ds_read_b128 v[72:75], v90 offset:17440
	ds_read_b128 v[108:111], v91 offset:32
	ds_read_b128 v[124:127], v90 offset:17472
	ds_read_b128 v[128:131], v91 offset:64
	ds_read_b128 v[112:115], v90 offset:17504
	ds_read_b128 v[116:119], v91 offset:96
	s_waitcnt lgkmcnt(6)
	v_mfma_f32_32x32x16_bf16 v[32:47], v[32:35], v[36:39], 0
	s_waitcnt lgkmcnt(4)
	v_mfma_f32_32x32x16_bf16 v[32:47], v[72:75], v[108:111], v[32:47]
	ds_read_b128 v[72:75], v90 offset:17536
	ds_read_b128 v[108:111], v91 offset:128
	s_waitcnt lgkmcnt(4)
	v_mfma_f32_32x32x16_bf16 v[32:47], v[124:127], v[128:131], v[32:47]
	ds_read_b128 v[124:127], v90 offset:17568
	ds_read_b128 v[128:131], v91 offset:160
	s_waitcnt lgkmcnt(4)
	v_mfma_f32_32x32x16_bf16 v[32:47], v[112:115], v[116:119], v[32:47]
	ds_read_b128 v[112:115], v90 offset:17600
	ds_read_b128 v[116:119], v91 offset:192
	s_waitcnt lgkmcnt(4)
	v_mfma_f32_32x32x16_bf16 v[32:47], v[72:75], v[108:111], v[32:47]
	ds_read_b128 v[72:75], v90 offset:17632
	ds_read_b128 v[108:111], v91 offset:224
	s_waitcnt lgkmcnt(4)
	v_mfma_f32_32x32x16_bf16 v[32:47], v[124:127], v[128:131], v[32:47]
	s_waitcnt lgkmcnt(2)
	v_mfma_f32_32x32x16_bf16 v[32:47], v[112:115], v[116:119], v[32:47]
	s_waitcnt lgkmcnt(0)
	v_mfma_f32_32x32x16_bf16 v[32:47], v[72:75], v[108:111], v[32:47]
	s_nop 11
	v_cndmask_b32_e64 v32, v32, 0, s[4:5]
	v_cndmask_b32_e64 v33, 0, v33, s[6:7]
	v_cndmask_b32_e64 v34, v34, 0, s[8:9]
	v_cndmask_b32_e64 v35, v35, 0, s[10:11]
	v_cndmask_b32_e64 v36, v36, 0, s[12:13]
	v_cndmask_b32_e64 v37, v37, 0, s[14:15]
	v_cndmask_b32_e64 v38, v38, 0, s[16:17]
	v_cndmask_b32_e64 v39, v39, 0, s[18:19]
	v_cndmask_b32_e64 v40, v40, 0, s[20:21]
	v_cndmask_b32_e64 v41, v41, 0, s[22:23]
	v_cndmask_b32_e64 v42, v42, 0, s[24:25]
	v_cndmask_b32_e64 v43, v43, 0, s[26:27]
	v_cndmask_b32_e64 v44, v44, 0, s[28:29]
	v_cndmask_b32_e64 v45, v45, 0, s[30:31]
	v_cndmask_b32_e64 v46, v46, 0, s[34:35]
	v_cndmask_b32_e64 v47, v47, 0, s[36:37]
	v_cvt_pk_bf16_f32 v32, v32, v33
	v_cvt_pk_bf16_f32 v33, v34, v35
	v_cvt_pk_bf16_f32 v34, v36, v37
	v_cvt_pk_bf16_f32 v35, v38, v39
	v_cvt_pk_bf16_f32 v36, v40, v41
	v_cvt_pk_bf16_f32 v37, v42, v43
	v_cvt_pk_bf16_f32 v38, v44, v45
	v_cvt_pk_bf16_f32 v39, v46, v47
	ds_write2_b64 v92, v[32:33], v[34:35] offset1:2
	ds_write2_b64 v92, v[36:37], v[38:39] offset0:4 offset1:6
.LBB0_2679:
	ds_read_b128 v[32:35], v93
	v_add_u32_e32 v107, v88, v156
	ds_read_b128 v[36:39], v107
	ds_read_b128 v[72:75], v93 offset:32
	ds_read_b128 v[108:111], v107 offset:32
	ds_read_b128 v[124:127], v93 offset:64
	ds_read_b128 v[128:131], v107 offset:64
	ds_read_b128 v[112:115], v93 offset:96
	ds_read_b128 v[116:119], v107 offset:96
	s_andn2_b64 vcc, exec, s[64:65]
	s_waitcnt lgkmcnt(6)
	v_mfma_f32_32x32x16_bf16 v[32:47], v[32:35], v[36:39], 0
	s_waitcnt lgkmcnt(4)
	v_mfma_f32_32x32x16_bf16 v[32:47], v[72:75], v[108:111], v[32:47]
	ds_read_b128 v[72:75], v93 offset:128
	ds_read_b128 v[108:111], v107 offset:128
	s_waitcnt lgkmcnt(4)
	v_mfma_f32_32x32x16_bf16 v[32:47], v[124:127], v[128:131], v[32:47]
	ds_read_b128 v[124:127], v93 offset:160
	ds_read_b128 v[128:131], v107 offset:160
	s_waitcnt lgkmcnt(4)
	v_mfma_f32_32x32x16_bf16 v[32:47], v[112:115], v[116:119], v[32:47]
	ds_read_b128 v[112:115], v93 offset:192
	ds_read_b128 v[116:119], v107 offset:192
	s_waitcnt lgkmcnt(4)
	v_mfma_f32_32x32x16_bf16 v[32:47], v[72:75], v[108:111], v[32:47]
	ds_read_b128 v[72:75], v93 offset:224
	ds_read_b128 v[108:111], v107 offset:224
	s_waitcnt lgkmcnt(4)
	v_mfma_f32_32x32x16_bf16 v[32:47], v[124:127], v[128:131], v[32:47]
	s_waitcnt lgkmcnt(2)
	v_mfma_f32_32x32x16_bf16 v[32:47], v[112:115], v[116:119], v[32:47]
	s_waitcnt lgkmcnt(0)
	s_barrier
	v_mfma_f32_32x32x16_bf16 v[32:47], v[72:75], v[108:111], v[32:47]
	v_cndmask_b32_e64 v72, 0, 1, s[64:65]
	v_cmp_ne_u32_e64 s[38:39], 1, v72
	s_cbranch_vccnz .LBB0_2681
	ds_read_b128 v[72:75], v97
	ds_read_b128 v[108:111], v98 offset:53248
	s_waitcnt lgkmcnt(0)
	v_mfma_f32_32x32x16_bf16 v[32:47], v[72:75], v[108:111], v[32:47]

.LBB0_2689:
	ds_read_b128 v[108:111], v94 offset:34816
	ds_read_b128 v[112:115], v98 offset:53248
	ds_read_b128 v[116:119], v94 offset:39424
	ds_read_b128 v[120:123], v94 offset:34848
	ds_read_b128 v[128:131], v98 offset:53280
	ds_read_b128 v[124:127], v94 offset:39456
	s_mov_b32 s38, 0xf800000
	s_waitcnt lgkmcnt(4)
	v_mfma_f32_32x32x16_bf16 v[0:15], v[108:111], v[112:115], v[0:15]
	s_waitcnt lgkmcnt(3)
	v_mfma_f32_32x32x16_bf16 v[16:31], v[116:119], v[112:115], v[16:31]
	ds_read_b128 v[108:111], v94 offset:34880
	ds_read_b128 v[112:115], v98 offset:53312
	ds_read_b128 v[116:119], v94 offset:39488
	s_waitcnt lgkmcnt(4)
	v_mfma_f32_32x32x16_bf16 v[0:15], v[120:123], v[128:131], v[0:15]
	s_waitcnt lgkmcnt(3)
	v_mfma_f32_32x32x16_bf16 v[16:31], v[124:127], v[128:131], v[16:31]
	ds_read_b128 v[120:123], v94 offset:34912
	ds_read_b128 v[124:127], v94 offset:39520
	s_waitcnt lgkmcnt(3)
	v_mfma_f32_32x32x16_bf16 v[0:15], v[108:111], v[112:115], v[0:15]
	s_waitcnt lgkmcnt(2)
	v_mfma_f32_32x32x16_bf16 v[16:31], v[116:119], v[112:115], v[16:31]
	s_waitcnt lgkmcnt(1)
	v_mfma_f32_32x32x16_bf16 v[0:15], v[120:123], v[72:75], v[0:15]
	ds_read_b128 v[108:111], v95
	ds_read_b128 v[116:119], v95 offset:32
	ds_read_b128 v[120:123], v95 offset:128
	s_waitcnt lgkmcnt(3)
	v_mfma_f32_32x32x16_bf16 v[16:31], v[124:127], v[72:75], v[16:31]
	ds_read_b128 v[72:75], v95 offset:160
	ds_read_b128 v[112:115], v95 offset:192
	s_waitcnt lgkmcnt(4)
	s_nop 3
	v_mul_f32_e64 v0, v0, v108
	v_mul_f32_e64 v1, v1, v109
	v_pk_mul_f32 v[2:3], v[2:3], v[110:111]
	ds_read_b128 v[108:111], v95 offset:64
	s_waitcnt lgkmcnt(4)
	v_pk_mul_f32 v[4:5], v[4:5], v[116:117]
	v_pk_mul_f32 v[6:7], v[6:7], v[118:119]
	s_waitcnt lgkmcnt(2)
	v_pk_mul_f32 v[20:21], v[20:21], v[72:73]
	v_pk_mul_f32 v[22:23], v[22:23], v[74:75]
	ds_read_b128 v[72:75], v95 offset:96
	ds_read_b128 v[116:119], v95 offset:224
	v_pk_mul_f32 v[16:17], v[16:17], v[120:121]
	v_pk_mul_f32 v[18:19], v[18:19], v[122:123]
	s_waitcnt lgkmcnt(2)
	v_pk_mul_f32 v[8:9], v[8:9], v[108:109]
	v_pk_mul_f32 v[10:11], v[10:11], v[110:111]
	s_waitcnt lgkmcnt(1)
	v_pk_mul_f32 v[12:13], v[12:13], v[72:73]
	v_pk_mul_f32 v[14:15], v[14:15], v[74:75]
	v_cvt_pk_bf16_f32 v72, v0, v1
	v_cvt_pk_bf16_f32 v73, v2, v3
	v_cvt_pk_bf16_f32 v108, v4, v5
	v_cvt_pk_bf16_f32 v109, v6, v7
	v_pk_mul_f32 v[24:25], v[24:25], v[112:113]
	v_pk_mul_f32 v[26:27], v[26:27], v[114:115]
	s_waitcnt lgkmcnt(0)
	v_pk_mul_f32 v[28:29], v[28:29], v[116:117]
	v_pk_mul_f32 v[30:31], v[30:31], v[118:119]
	v_cvt_pk_bf16_f32 v74, v16, v17
	v_cvt_pk_bf16_f32 v75, v18, v19
	v_cvt_pk_bf16_f32 v110, v20, v21
	v_cvt_pk_bf16_f32 v111, v22, v23
	ds_write2_b64 v89, v[72:73], v[108:109] offset1:2
	ds_write2_b64 v89, v[74:75], v[110:111] offset0:8 offset1:10
	v_cvt_pk_bf16_f32 v72, v8, v9
	v_cvt_pk_bf16_f32 v73, v10, v11
	v_cvt_pk_bf16_f32 v108, v12, v13
	v_cvt_pk_bf16_f32 v109, v14, v15
	v_cvt_pk_bf16_f32 v74, v24, v25
	v_cvt_pk_bf16_f32 v75, v26, v27
	v_cvt_pk_bf16_f32 v110, v28, v29
	v_cvt_pk_bf16_f32 v111, v30, v31
	ds_write2_b64 v89, v[72:73], v[108:109] offset0:4 offset1:6
	ds_write2_b64 v89, v[74:75], v[110:111] offset0:12 offset1:14
	ds_write2_b32 v96, v32, v33 offset1:132
	v_add_u32_e32 v32, 0x400, v96
	ds_write2_b32 v32, v34, v35 offset0:8 offset1:140
	v_add_u32_e32 v32, 0x1000, v96
	ds_write2_b32 v32, v36, v37 offset0:32 offset1:164
	v_add_u32_e32 v32, 0x1400, v96
	ds_write2_b32 v32, v38, v39 offset0:40 offset1:172
	v_add_u32_e32 v32, 0x2000, v96
	ds_write2_b32 v32, v40, v41 offset0:64 offset1:196
	v_add_u32_e32 v32, 0x2400, v96
	ds_write2_b32 v32, v42, v43 offset0:72 offset1:204
	v_add_u32_e32 v32, 0x3000, v96
	ds_write2_b32 v32, v44, v45 offset0:96 offset1:228
	v_add_u32_e32 v32, 0x3400, v96
	ds_write2_b32 v32, v46, v47 offset0:104 offset1:236
	s_waitcnt lgkmcnt(0)
	s_barrier
	ds_read_b128 v[32:35], v163
	ds_read_b128 v[36:39], v163 offset:16
	ds_read_b128 v[40:43], v163 offset:32
	ds_read_b128 v[44:47], v163 offset:48
	s_waitcnt lgkmcnt(3)
	v_pk_mul_f32 v[72:73], v[34:35], v[34:35]
	v_pk_mul_f32 v[74:75], v[32:33], v[32:33]
	s_waitcnt lgkmcnt(0)
	v_mul_f32_e32 v107, v44, v44
	v_pk_mov_b32 v[108:109], v[74:75], v[72:73] op_sel:[1,0]
	v_mov_b32_e32 v75, v73
	v_pk_add_f32 v[72:73], v[108:109], v[74:75]
	v_pk_mul_f32 v[74:75], v[38:39], v[38:39]
	v_pk_mul_f32 v[108:109], v[36:37], v[36:37]
	v_pk_add_f32 v[72:73], v[72:73], v[72:73] op_sel:[0,1] op_sel_hi:[1,0]
	v_pk_mov_b32 v[110:111], v[108:109], v[74:75] op_sel:[1,0]
	v_mov_b32_e32 v109, v75
	v_pk_add_f32 v[74:75], v[110:111], v[108:109]
	v_mul_f32_e32 v108, v45, v45
	v_pk_add_f32 v[74:75], v[74:75], v[74:75] op_sel:[0,1] op_sel_hi:[1,0]
	v_mov_b32_e32 v73, v107
	v_mov_b32_e32 v75, v108
	v_pk_add_f32 v[72:73], v[72:73], v[74:75]
	v_mul_f32_e32 v74, v41, v41
	v_mul_f32_e32 v109, v46, v46
	v_pk_fma_f32 v[74:75], v[40:41], v[40:41], v[74:75] op_sel_hi:[1,1,0]
	v_mul_f32_e32 v108, v43, v43
	v_mul_f32_e32 v110, v47, v47
	v_mov_b32_e32 v75, v109
	v_pk_fma_f32 v[108:109], v[42:43], v[42:43], v[108:109] op_sel_hi:[1,1,0]
	s_nop 0
	v_mov_b32_e32 v109, v110
	v_pk_add_f32 v[74:75], v[74:75], v[108:109]
	s_nop 0
	v_pk_add_f32 v[72:73], v[72:73], v[74:75]
	s_nop 0
	v_add_f32_e32 v72, v72, v73
	s_nop 1
	v_add_f32_dpp v72, v72, v72 quad_perm:[1,0,3,2] row_mask:0xf bank_mask:0xf bound_ctrl:1
	s_nop 1
	v_add_f32_dpp v72, v72, v72 quad_perm:[2,3,0,1] row_mask:0xf bank_mask:0xf bound_ctrl:1
	s_nop 1
	v_add_f32_dpp v72, v72, v72 row_half_mirror row_mask:0xf bank_mask:0xf bound_ctrl:1
	v_fmamk_f32 v72, v72, 0x3c000000, v178
	v_cmp_gt_f32_e32 vcc, s38, v72
	v_mul_f32_e32 v73, 0x4f800000, v72
	s_nop 0
	v_cndmask_b32_e32 v72, v72, v73, vcc
	v_sqrt_f32_e32 v73, v72
	s_nop 0
	v_add_u32_e32 v74, -1, v73
	v_fma_f32 v75, -v74, v73, v72
	v_cmp_ge_f32_e64 s[38:39], 0, v75
	v_add_u32_e32 v75, 1, v73
	s_nop 0
	v_cndmask_b32_e64 v74, v73, v74, s[38:39]
	v_fma_f32 v73, -v75, v73, v72
	v_cmp_lt_f32_e64 s[38:39], 0, v73
	s_nop 1
	v_cndmask_b32_e64 v73, v74, v75, s[38:39]
	v_mul_f32_e32 v74, 0x37800000, v73
	v_cndmask_b32_e32 v73, v73, v74, vcc
	v_cmp_class_f32_e32 vcc, v72, v179
	s_nop 1
	v_cndmask_b32_e32 v72, v73, v72, vcc
	v_div_scale_f32 v73, s[38:39], v72, v72, 1.0
	v_rcp_f32_e32 v74, v73
	s_nop 0
	v_fma_f32 v75, -v73, v74, 1.0
	v_fmac_f32_e32 v74, v75, v74
	v_div_scale_f32 v75, vcc, 1.0, v72, 1.0
	v_mul_f32_e32 v107, v75, v74
	v_fma_f32 v108, -v73, v107, v75
	v_fmac_f32_e32 v107, v108, v74
	v_fma_f32 v73, -v73, v107, v75
	v_div_fmas_f32 v73, v73, v74, v107
	v_div_fixup_f32 v72, v73, v72, 1.0
	v_pk_mul_f32 v[32:33], v[32:33], v[72:73] op_sel_hi:[1,0]
	s_waitcnt vmcnt(1)
	v_lshlrev_b32_e32 v74, 16, v52
	v_and_b32_e32 v75, 0xffff0000, v52
	s_waitcnt vmcnt(0)
	v_pk_mul_f32 v[32:33], v[68:69], v[32:33]
	v_pk_mul_f32 v[34:35], v[34:35], v[72:73] op_sel_hi:[1,0]
	v_pk_mul_f32 v[32:33], v[32:33], v[74:75]
	v_lshlrev_b32_e32 v74, 16, v53
	v_and_b32_e32 v75, 0xffff0000, v53
	v_pk_mul_f32 v[34:35], v[70:71], v[34:35]
	v_pk_mul_f32 v[36:37], v[36:37], v[72:73] op_sel_hi:[1,0]
	v_pk_mul_f32 v[34:35], v[34:35], v[74:75]
	v_cvt_pk_bf16_f32 v32, v32, v33
	v_cvt_pk_bf16_f32 v33, v34, v35
	v_lshlrev_b32_e32 v34, 16, v54
	v_and_b32_e32 v35, 0xffff0000, v54
	v_pk_mul_f32 v[36:37], v[64:65], v[36:37]
	v_pk_mul_f32 v[38:39], v[38:39], v[72:73] op_sel_hi:[1,0]
	v_pk_mul_f32 v[34:35], v[36:37], v[34:35]
	v_lshlrev_b32_e32 v36, 16, v55
	v_and_b32_e32 v37, 0xffff0000, v55
	v_pk_mul_f32 v[38:39], v[66:67], v[38:39]
	v_cvt_pk_bf16_f32 v34, v34, v35
	v_pk_mul_f32 v[36:37], v[38:39], v[36:37]
	v_pk_mul_f32 v[38:39], v[40:41], v[72:73] op_sel_hi:[1,0]
	v_cvt_pk_bf16_f32 v35, v36, v37
	v_lshlrev_b32_e32 v36, 16, v48
	v_and_b32_e32 v37, 0xffff0000, v48
	v_pk_mul_f32 v[38:39], v[60:61], v[38:39]
	v_pk_mul_f32 v[40:41], v[42:43], v[72:73] op_sel_hi:[1,0]
	v_pk_mul_f32 v[36:37], v[38:39], v[36:37]
	v_lshlrev_b32_e32 v38, 16, v49
	v_and_b32_e32 v39, 0xffff0000, v49
	v_pk_mul_f32 v[40:41], v[62:63], v[40:41]
	v_cvt_pk_bf16_f32 v36, v36, v37
	v_pk_mul_f32 v[38:39], v[40:41], v[38:39]
	v_pk_mul_f32 v[40:41], v[44:45], v[72:73] op_sel_hi:[1,0]
	v_cvt_pk_bf16_f32 v37, v38, v39
	v_lshlrev_b32_e32 v38, 16, v50
	v_and_b32_e32 v39, 0xffff0000, v50
	v_pk_mul_f32 v[40:41], v[56:57], v[40:41]
	v_pk_mul_f32 v[42:43], v[46:47], v[72:73] op_sel_hi:[1,0]
	v_pk_mul_f32 v[38:39], v[40:41], v[38:39]
	v_lshlrev_b32_e32 v40, 16, v51
	v_and_b32_e32 v41, 0xffff0000, v51
	v_pk_mul_f32 v[42:43], v[58:59], v[42:43]
	v_cvt_pk_bf16_f32 v38, v38, v39
	v_pk_mul_f32 v[40:41], v[42:43], v[40:41]
	s_nop 0
	v_cvt_pk_bf16_f32 v39, v40, v41
	v_lshl_add_u64 v[40:41], s[42:43], 0, v[78:79]
	v_add_co_u32_e32 v40, vcc, 0x10400000, v40
	s_nop 1
	v_addc_co_u32_e32 v41, vcc, 0, v41, vcc
	s_andn2_b64 vcc, exec, s[70:71]
	global_store_dwordx4 v[40:41], v[32:35], off
	global_store_dwordx4 v[40:41], v[36:39], off offset:16
	s_cbranch_vccnz .LBB0_2664
	v_lshl_add_u64 v[32:33], s[42:43], 0, v[76:77]
	s_mov_b64 s[38:39], 0x5310000
	v_lshl_add_u64 v[34:35], v[32:33], 0, s[38:39]
	v_add_co_u32_e32 v32, vcc, 0x5310000, v32
	s_nop 1
	v_addc_co_u32_e32 v33, vcc, 0, v33, vcc
	global_load_dwordx4 v[52:55], v[32:33], off
	global_load_dwordx4 v[48:51], v[34:35], off offset:16
	s_branch .LBB0_2664

.LBB0_3049:
	s_andn2_b64 vcc, exec, s[60:61]
	s_cbranch_vccnz .LBB0_3051
	ds_read_b128 v[32:35], v90 offset:17408
	ds_read_b128 v[36:39], v91
	ds_read_b128 v[72:75], v90 offset:17440
	ds_read_b128 v[108:111], v91 offset:32
	ds_read_b128 v[124:127], v90 offset:17472
	ds_read_b128 v[128:131], v91 offset:64
	ds_read_b128 v[112:115], v90 offset:17504
	ds_read_b128 v[116:119], v91 offset:96
	s_waitcnt lgkmcnt(6)
	v_mfma_f32_32x32x16_bf16 v[32:47], v[32:35], v[36:39], 0
	s_waitcnt lgkmcnt(4)
	v_mfma_f32_32x32x16_bf16 v[32:47], v[72:75], v[108:111], v[32:47]
	ds_read_b128 v[72:75], v90 offset:17536
	ds_read_b128 v[108:111], v91 offset:128
	s_waitcnt lgkmcnt(4)
	v_mfma_f32_32x32x16_bf16 v[32:47], v[124:127], v[128:131], v[32:47]
	ds_read_b128 v[124:127], v90 offset:17568
	ds_read_b128 v[128:131], v91 offset:160
	s_waitcnt lgkmcnt(4)
	v_mfma_f32_32x32x16_bf16 v[32:47], v[112:115], v[116:119], v[32:47]
	ds_read_b128 v[112:115], v90 offset:17600
	ds_read_b128 v[116:119], v91 offset:192
	s_waitcnt lgkmcnt(4)
	v_mfma_f32_32x32x16_bf16 v[32:47], v[72:75], v[108:111], v[32:47]
	ds_read_b128 v[72:75], v90 offset:17632
	ds_read_b128 v[108:111], v91 offset:224
	s_waitcnt lgkmcnt(4)
	v_mfma_f32_32x32x16_bf16 v[32:47], v[124:127], v[128:131], v[32:47]
	s_waitcnt lgkmcnt(2)
	v_mfma_f32_32x32x16_bf16 v[32:47], v[112:115], v[116:119], v[32:47]
	s_waitcnt lgkmcnt(0)
	v_mfma_f32_32x32x16_bf16 v[32:47], v[72:75], v[108:111], v[32:47]
	s_nop 11
	v_cndmask_b32_e64 v32, v32, 0, s[4:5]
	v_cndmask_b32_e64 v33, 0, v33, s[6:7]
	v_cndmask_b32_e64 v34, v34, 0, s[8:9]
	v_cndmask_b32_e64 v35, v35, 0, s[10:11]
	v_cndmask_b32_e64 v36, v36, 0, s[12:13]
	v_cndmask_b32_e64 v37, v37, 0, s[14:15]
	v_cndmask_b32_e64 v38, v38, 0, s[16:17]
	v_cndmask_b32_e64 v39, v39, 0, s[18:19]
	v_cndmask_b32_e64 v40, v40, 0, s[20:21]
	v_cndmask_b32_e64 v41, v41, 0, s[22:23]
	v_cndmask_b32_e64 v42, v42, 0, s[24:25]
	v_cndmask_b32_e64 v43, v43, 0, s[26:27]
	v_cndmask_b32_e64 v44, v44, 0, s[28:29]
	v_cndmask_b32_e64 v45, v45, 0, s[30:31]
	v_cndmask_b32_e64 v46, v46, 0, s[34:35]
	v_cndmask_b32_e64 v47, v47, 0, s[36:37]
	v_cvt_pk_bf16_f32 v32, v32, v33
	v_cvt_pk_bf16_f32 v33, v34, v35
	v_cvt_pk_bf16_f32 v34, v36, v37
	v_cvt_pk_bf16_f32 v35, v38, v39
	v_cvt_pk_bf16_f32 v36, v40, v41
	v_cvt_pk_bf16_f32 v37, v42, v43
	v_cvt_pk_bf16_f32 v38, v44, v45
	v_cvt_pk_bf16_f32 v39, v46, v47
	ds_write2_b64 v92, v[32:33], v[34:35] offset1:2
	ds_write2_b64 v92, v[36:37], v[38:39] offset0:4 offset1:6
.LBB0_3051:
	ds_read_b128 v[32:35], v93
	v_add_u32_e32 v107, v88, v156
	ds_read_b128 v[36:39], v107
	ds_read_b128 v[72:75], v93 offset:32
	ds_read_b128 v[108:111], v107 offset:32
	ds_read_b128 v[124:127], v93 offset:64
	ds_read_b128 v[128:131], v107 offset:64
	ds_read_b128 v[112:115], v93 offset:96
	ds_read_b128 v[116:119], v107 offset:96
	s_andn2_b64 vcc, exec, s[62:63]
	s_waitcnt lgkmcnt(6)
	v_mfma_f32_32x32x16_bf16 v[32:47], v[32:35], v[36:39], 0
	s_waitcnt lgkmcnt(4)
	v_mfma_f32_32x32x16_bf16 v[32:47], v[72:75], v[108:111], v[32:47]
	ds_read_b128 v[72:75], v93 offset:128
	ds_read_b128 v[108:111], v107 offset:128
	s_waitcnt lgkmcnt(4)
	v_mfma_f32_32x32x16_bf16 v[32:47], v[124:127], v[128:131], v[32:47]
	ds_read_b128 v[124:127], v93 offset:160
	ds_read_b128 v[128:131], v107 offset:160
	s_waitcnt lgkmcnt(4)
	v_mfma_f32_32x32x16_bf16 v[32:47], v[112:115], v[116:119], v[32:47]
	ds_read_b128 v[112:115], v93 offset:192
	ds_read_b128 v[116:119], v107 offset:192
	s_waitcnt lgkmcnt(4)
	v_mfma_f32_32x32x16_bf16 v[32:47], v[72:75], v[108:111], v[32:47]
	ds_read_b128 v[72:75], v93 offset:224
	ds_read_b128 v[108:111], v107 offset:224
	s_waitcnt lgkmcnt(4)
	v_mfma_f32_32x32x16_bf16 v[32:47], v[124:127], v[128:131], v[32:47]
	s_waitcnt lgkmcnt(2)
	v_mfma_f32_32x32x16_bf16 v[32:47], v[112:115], v[116:119], v[32:47]
	s_waitcnt lgkmcnt(0)
	s_barrier
	v_mfma_f32_32x32x16_bf16 v[32:47], v[72:75], v[108:111], v[32:47]
	v_cndmask_b32_e64 v72, 0, 1, s[62:63]
	v_cmp_ne_u32_e64 s[38:39], 1, v72
	s_cbranch_vccnz .LBB0_3053
	ds_read_b128 v[72:75], v97
	ds_read_b128 v[108:111], v98 offset:53248
	s_waitcnt lgkmcnt(0)
	v_mfma_f32_32x32x16_bf16 v[32:47], v[72:75], v[108:111], v[32:47]

.LBB0_3061:
	ds_read_b128 v[108:111], v94 offset:34816
	ds_read_b128 v[112:115], v98 offset:53248
	ds_read_b128 v[116:119], v94 offset:39424
	ds_read_b128 v[120:123], v94 offset:34848
	ds_read_b128 v[128:131], v98 offset:53280
	ds_read_b128 v[124:127], v94 offset:39456
	s_mov_b32 s38, 0xf800000
	s_waitcnt lgkmcnt(4)
	v_mfma_f32_32x32x16_bf16 v[0:15], v[108:111], v[112:115], v[0:15]
	s_waitcnt lgkmcnt(3)
	v_mfma_f32_32x32x16_bf16 v[16:31], v[116:119], v[112:115], v[16:31]
	ds_read_b128 v[108:111], v94 offset:34880
	ds_read_b128 v[112:115], v98 offset:53312
	ds_read_b128 v[116:119], v94 offset:39488
	s_waitcnt lgkmcnt(4)
	v_mfma_f32_32x32x16_bf16 v[0:15], v[120:123], v[128:131], v[0:15]
	s_waitcnt lgkmcnt(3)
	v_mfma_f32_32x32x16_bf16 v[16:31], v[124:127], v[128:131], v[16:31]
	ds_read_b128 v[120:123], v94 offset:34912
	ds_read_b128 v[124:127], v94 offset:39520
	s_waitcnt lgkmcnt(3)
	v_mfma_f32_32x32x16_bf16 v[0:15], v[108:111], v[112:115], v[0:15]
	s_waitcnt lgkmcnt(2)
	v_mfma_f32_32x32x16_bf16 v[16:31], v[116:119], v[112:115], v[16:31]
	s_waitcnt lgkmcnt(1)
	v_mfma_f32_32x32x16_bf16 v[0:15], v[120:123], v[72:75], v[0:15]
	ds_read_b128 v[108:111], v95
	ds_read_b128 v[116:119], v95 offset:32
	ds_read_b128 v[120:123], v95 offset:128
	s_waitcnt lgkmcnt(3)
	v_mfma_f32_32x32x16_bf16 v[16:31], v[124:127], v[72:75], v[16:31]
	ds_read_b128 v[72:75], v95 offset:160
	ds_read_b128 v[112:115], v95 offset:192
	s_waitcnt lgkmcnt(4)
	s_nop 3
	v_mul_f32_e64 v0, v0, v108
	v_mul_f32_e64 v1, v1, v109
	v_pk_mul_f32 v[2:3], v[2:3], v[110:111]
	ds_read_b128 v[108:111], v95 offset:64
	s_waitcnt lgkmcnt(4)
	v_pk_mul_f32 v[4:5], v[4:5], v[116:117]
	v_pk_mul_f32 v[6:7], v[6:7], v[118:119]
	s_waitcnt lgkmcnt(2)
	v_pk_mul_f32 v[20:21], v[20:21], v[72:73]
	v_pk_mul_f32 v[22:23], v[22:23], v[74:75]
	ds_read_b128 v[72:75], v95 offset:96
	ds_read_b128 v[116:119], v95 offset:224
	v_pk_mul_f32 v[16:17], v[16:17], v[120:121]
	v_pk_mul_f32 v[18:19], v[18:19], v[122:123]
	s_waitcnt lgkmcnt(2)
	v_pk_mul_f32 v[8:9], v[8:9], v[108:109]
	v_pk_mul_f32 v[10:11], v[10:11], v[110:111]
	s_waitcnt lgkmcnt(1)
	v_pk_mul_f32 v[12:13], v[12:13], v[72:73]
	v_pk_mul_f32 v[14:15], v[14:15], v[74:75]
	v_cvt_pk_bf16_f32 v72, v0, v1
	v_cvt_pk_bf16_f32 v73, v2, v3
	v_cvt_pk_bf16_f32 v108, v4, v5
	v_cvt_pk_bf16_f32 v109, v6, v7
	v_pk_mul_f32 v[24:25], v[24:25], v[112:113]
	v_pk_mul_f32 v[26:27], v[26:27], v[114:115]
	s_waitcnt lgkmcnt(0)
	v_pk_mul_f32 v[28:29], v[28:29], v[116:117]
	v_pk_mul_f32 v[30:31], v[30:31], v[118:119]
	v_cvt_pk_bf16_f32 v74, v16, v17
	v_cvt_pk_bf16_f32 v75, v18, v19
	v_cvt_pk_bf16_f32 v110, v20, v21
	v_cvt_pk_bf16_f32 v111, v22, v23
	ds_write2_b64 v89, v[72:73], v[108:109] offset1:2
	ds_write2_b64 v89, v[74:75], v[110:111] offset0:8 offset1:10
	v_cvt_pk_bf16_f32 v72, v8, v9
	v_cvt_pk_bf16_f32 v73, v10, v11
	v_cvt_pk_bf16_f32 v108, v12, v13
	v_cvt_pk_bf16_f32 v109, v14, v15
	v_cvt_pk_bf16_f32 v74, v24, v25
	v_cvt_pk_bf16_f32 v75, v26, v27
	v_cvt_pk_bf16_f32 v110, v28, v29
	v_cvt_pk_bf16_f32 v111, v30, v31
	ds_write2_b64 v89, v[72:73], v[108:109] offset0:4 offset1:6
	ds_write2_b64 v89, v[74:75], v[110:111] offset0:12 offset1:14
	ds_write2_b32 v96, v32, v33 offset1:132
	v_add_u32_e32 v32, 0x400, v96
	ds_write2_b32 v32, v34, v35 offset0:8 offset1:140
	v_add_u32_e32 v32, 0x1000, v96
	ds_write2_b32 v32, v36, v37 offset0:32 offset1:164
	v_add_u32_e32 v32, 0x1400, v96
	ds_write2_b32 v32, v38, v39 offset0:40 offset1:172
	v_add_u32_e32 v32, 0x2000, v96
	ds_write2_b32 v32, v40, v41 offset0:64 offset1:196
	v_add_u32_e32 v32, 0x2400, v96
	ds_write2_b32 v32, v42, v43 offset0:72 offset1:204
	v_add_u32_e32 v32, 0x3000, v96
	ds_write2_b32 v32, v44, v45 offset0:96 offset1:228
	v_add_u32_e32 v32, 0x3400, v96
	ds_write2_b32 v32, v46, v47 offset0:104 offset1:236
	s_waitcnt lgkmcnt(0)
	s_barrier
	ds_read_b128 v[32:35], v163
	ds_read_b128 v[36:39], v163 offset:16
	ds_read_b128 v[40:43], v163 offset:32
	ds_read_b128 v[44:47], v163 offset:48
	s_waitcnt lgkmcnt(3)
	v_pk_mul_f32 v[72:73], v[34:35], v[34:35]
	v_pk_mul_f32 v[74:75], v[32:33], v[32:33]
	s_waitcnt lgkmcnt(0)
	v_mul_f32_e32 v107, v44, v44
	v_pk_mov_b32 v[108:109], v[74:75], v[72:73] op_sel:[1,0]
	v_mov_b32_e32 v75, v73
	v_pk_add_f32 v[72:73], v[108:109], v[74:75]
	v_pk_mul_f32 v[74:75], v[38:39], v[38:39]
	v_pk_mul_f32 v[108:109], v[36:37], v[36:37]
	v_pk_add_f32 v[72:73], v[72:73], v[72:73] op_sel:[0,1] op_sel_hi:[1,0]
	v_pk_mov_b32 v[110:111], v[108:109], v[74:75] op_sel:[1,0]
	v_mov_b32_e32 v109, v75
	v_pk_add_f32 v[74:75], v[110:111], v[108:109]
	v_mul_f32_e32 v108, v45, v45
	v_pk_add_f32 v[74:75], v[74:75], v[74:75] op_sel:[0,1] op_sel_hi:[1,0]
	v_mov_b32_e32 v73, v107
	v_mov_b32_e32 v75, v108
	v_pk_add_f32 v[72:73], v[72:73], v[74:75]
	v_mul_f32_e32 v74, v41, v41
	v_mul_f32_e32 v109, v46, v46
	v_pk_fma_f32 v[74:75], v[40:41], v[40:41], v[74:75] op_sel_hi:[1,1,0]
	v_mul_f32_e32 v108, v43, v43
	v_mul_f32_e32 v110, v47, v47
	v_mov_b32_e32 v75, v109
	v_pk_fma_f32 v[108:109], v[42:43], v[42:43], v[108:109] op_sel_hi:[1,1,0]
	s_nop 0
	v_mov_b32_e32 v109, v110
	v_pk_add_f32 v[74:75], v[74:75], v[108:109]
	s_nop 0
	v_pk_add_f32 v[72:73], v[72:73], v[74:75]
	s_nop 0
	v_add_f32_e32 v72, v72, v73
	s_nop 1
	v_add_f32_dpp v72, v72, v72 quad_perm:[1,0,3,2] row_mask:0xf bank_mask:0xf bound_ctrl:1
	s_nop 1
	v_add_f32_dpp v72, v72, v72 quad_perm:[2,3,0,1] row_mask:0xf bank_mask:0xf bound_ctrl:1
	s_nop 1
	v_add_f32_dpp v72, v72, v72 row_half_mirror row_mask:0xf bank_mask:0xf bound_ctrl:1
	v_fmamk_f32 v72, v72, 0x3c000000, v178
	v_cmp_gt_f32_e32 vcc, s38, v72
	v_mul_f32_e32 v73, 0x4f800000, v72
	s_nop 0
	v_cndmask_b32_e32 v72, v72, v73, vcc
	v_sqrt_f32_e32 v73, v72
	s_nop 0
	v_add_u32_e32 v74, -1, v73
	v_fma_f32 v75, -v74, v73, v72
	v_cmp_ge_f32_e64 s[38:39], 0, v75
	v_add_u32_e32 v75, 1, v73
	s_nop 0
	v_cndmask_b32_e64 v74, v73, v74, s[38:39]
	v_fma_f32 v73, -v75, v73, v72
	v_cmp_lt_f32_e64 s[38:39], 0, v73
	s_nop 1
	v_cndmask_b32_e64 v73, v74, v75, s[38:39]
	v_mul_f32_e32 v74, 0x37800000, v73
	v_cndmask_b32_e32 v73, v73, v74, vcc
	v_cmp_class_f32_e32 vcc, v72, v179
	s_nop 1
	v_cndmask_b32_e32 v72, v73, v72, vcc
	v_div_scale_f32 v73, s[38:39], v72, v72, 1.0
	v_rcp_f32_e32 v74, v73
	s_nop 0
	v_fma_f32 v75, -v73, v74, 1.0
	v_fmac_f32_e32 v74, v75, v74
	v_div_scale_f32 v75, vcc, 1.0, v72, 1.0
	v_mul_f32_e32 v107, v75, v74
	v_fma_f32 v108, -v73, v107, v75
	v_fmac_f32_e32 v107, v108, v74
	v_fma_f32 v73, -v73, v107, v75
	v_div_fmas_f32 v73, v73, v74, v107
	v_div_fixup_f32 v72, v73, v72, 1.0
	v_pk_mul_f32 v[32:33], v[32:33], v[72:73] op_sel_hi:[1,0]
	s_waitcnt vmcnt(1)
	v_lshlrev_b32_e32 v74, 16, v52
	v_and_b32_e32 v75, 0xffff0000, v52
	s_waitcnt vmcnt(0)
	v_pk_mul_f32 v[32:33], v[68:69], v[32:33]
	v_pk_mul_f32 v[34:35], v[34:35], v[72:73] op_sel_hi:[1,0]
	v_pk_mul_f32 v[32:33], v[32:33], v[74:75]
	v_lshlrev_b32_e32 v74, 16, v53
	v_and_b32_e32 v75, 0xffff0000, v53
	v_pk_mul_f32 v[34:35], v[70:71], v[34:35]
	v_pk_mul_f32 v[36:37], v[36:37], v[72:73] op_sel_hi:[1,0]
	v_pk_mul_f32 v[34:35], v[34:35], v[74:75]
	v_cvt_pk_bf16_f32 v32, v32, v33
	v_cvt_pk_bf16_f32 v33, v34, v35
	v_lshlrev_b32_e32 v34, 16, v54
	v_and_b32_e32 v35, 0xffff0000, v54
	v_pk_mul_f32 v[36:37], v[64:65], v[36:37]
	v_pk_mul_f32 v[38:39], v[38:39], v[72:73] op_sel_hi:[1,0]
	v_pk_mul_f32 v[34:35], v[36:37], v[34:35]
	v_lshlrev_b32_e32 v36, 16, v55
	v_and_b32_e32 v37, 0xffff0000, v55
	v_pk_mul_f32 v[38:39], v[66:67], v[38:39]
	v_cvt_pk_bf16_f32 v34, v34, v35
	v_pk_mul_f32 v[36:37], v[38:39], v[36:37]
	v_pk_mul_f32 v[38:39], v[40:41], v[72:73] op_sel_hi:[1,0]
	v_cvt_pk_bf16_f32 v35, v36, v37
	v_lshlrev_b32_e32 v36, 16, v48
	v_and_b32_e32 v37, 0xffff0000, v48
	v_pk_mul_f32 v[38:39], v[60:61], v[38:39]
	v_pk_mul_f32 v[40:41], v[42:43], v[72:73] op_sel_hi:[1,0]
	v_pk_mul_f32 v[36:37], v[38:39], v[36:37]
	v_lshlrev_b32_e32 v38, 16, v49
	v_and_b32_e32 v39, 0xffff0000, v49
	v_pk_mul_f32 v[40:41], v[62:63], v[40:41]
	v_cvt_pk_bf16_f32 v36, v36, v37
	v_pk_mul_f32 v[38:39], v[40:41], v[38:39]
	v_pk_mul_f32 v[40:41], v[44:45], v[72:73] op_sel_hi:[1,0]
	v_cvt_pk_bf16_f32 v37, v38, v39
	v_lshlrev_b32_e32 v38, 16, v50
	v_and_b32_e32 v39, 0xffff0000, v50
	v_pk_mul_f32 v[40:41], v[56:57], v[40:41]
	v_pk_mul_f32 v[42:43], v[46:47], v[72:73] op_sel_hi:[1,0]
	v_pk_mul_f32 v[38:39], v[40:41], v[38:39]
	v_lshlrev_b32_e32 v40, 16, v51
	v_and_b32_e32 v41, 0xffff0000, v51
	v_pk_mul_f32 v[42:43], v[58:59], v[42:43]
	v_cvt_pk_bf16_f32 v38, v38, v39
	v_pk_mul_f32 v[40:41], v[42:43], v[40:41]
	s_nop 0
	v_cvt_pk_bf16_f32 v39, v40, v41
	v_lshl_add_u64 v[40:41], s[42:43], 0, v[78:79]
	v_add_co_u32_e32 v40, vcc, 0x10400000, v40
	s_nop 1
	v_addc_co_u32_e32 v41, vcc, 0, v41, vcc
	s_andn2_b64 vcc, exec, s[68:69]
	global_store_dwordx4 v[40:41], v[32:35], off
	global_store_dwordx4 v[40:41], v[36:39], off offset:16
	s_cbranch_vccnz .LBB0_3036
	v_lshl_add_u64 v[32:33], s[42:43], 0, v[76:77]
	s_mov_b64 s[38:39], 0x5310000
	v_lshl_add_u64 v[34:35], v[32:33], 0, s[38:39]
	v_add_co_u32_e32 v32, vcc, 0x5310000, v32
	s_nop 1
	v_addc_co_u32_e32 v33, vcc, 0, v33, vcc
	global_load_dwordx4 v[52:55], v[32:33], off
	global_load_dwordx4 v[48:51], v[34:35], off offset:16
	s_branch .LBB0_3036
